# GEMM unit scheduler: idx / gsz and idx % gsz by shift and mask (gsz is always 8), run-time division removed from the unit head of the in/up GEMMs
# speedup vs baseline: 1.0034x; 1.0034x over previous
.LBB0_203:
	s_add_i32 s96, s96, 1
	s_mul_i32 s9, s96, s97
	s_mul_hi_u32 s10, s96, s62
	s_add_i32 s10, s10, s9
	s_mul_i32 s9, s96, s62
	s_add_u32 s56, s9, s2
	s_addc_u32 s57, s10, s4
	v_cmp_gt_i64_e32 vcc, s[56:57], v[196:197]
	v_cmp_lt_i64_e64 s[38:39], s[56:57], v[194:195]
	s_cbranch_vccnz .LBB0_205
	s_ashr_i32 s9, s56, 31
	s_lshr_b32 s9, s9, 29
	s_add_i32 s9, s56, s9
	s_ashr_i32 s10, s9, 3
	s_and_b32 s9, s9, -8
	s_sub_i32 s9, s56, s9
	s_cmp_lt_i32 s9, 0
	s_movk_i32 s11, 0x79
	s_cselect_b32 s11, s11, 0x78
	s_mul_i32 s9, s9, s11
	s_add_i32 s9, s9, s10
	s_mul_hi_i32 s10, s9, 0x88888889
	s_add_i32 s10, s10, s9
	s_lshr_b32 s11, s10, 31
	s_ashr_i32 s10, s10, 6
	s_add_i32 s10, s10, s11
	s_lshl_b32 s11, s10, 3
	s_mulk_i32 s10, 0x78
	s_sub_i32 s9, s9, s10
	s_ashr_i32 s52, s9, 3
	s_and_b32 s9, s9, 7
	s_add_i32 s54, s11, s9

.LBB0_1142:
	s_ashr_i32 s5, s5, 3
	s_add_i32 s5, s7, s5
	s_ashr_i32 s6, s5, 31
	s_lshr_b32 s6, s6, 25
	s_add_i32 s6, s5, s6
	s_ashr_i32 s7, s6, 7
	s_lshl_b32 s7, s7, 3
	s_and_b32 s6, s6, 0xffffff80
	s_sub_i32 s5, s5, s6
	s_ashr_i32 s46, s5, 3
	s_and_b32 s5, s5, 7
	s_add_i32 s48, s7, s5
